# H4 + in-proj: all four lower-bound loads of the f-tile epilogue issued at tile start (no load round trip and no vmcnt(0) drain in that epilogue)
# baseline (speedup 1.0000x reference)
; #define PG8_STAGE(bufoff, gbase, voff) do { _Pragma("unroll") for (int _i = 0; _i < 2; ++_i) \
;         __builtin_amdgcn_global_load_lds((const unsigned*)((const char*)(gbase) + (voff)[_i]), (PG8_LAS unsigned*)(lds + (bufoff) + ldsw + _i * 8192), 16, 0, 0); } while (0)
; #define PG8_LDA(dst, b, h) do { _Pragma("unroll") for (int m = 0; m < 4; ++m) _Pragma("unroll") for (int k = 0; k < 2; ++k) dst[m][k] = *(const PG8_LAS bf16x8*)(lds + PG8_SA(b, h) + aoff + m * 2048 + k * 1024); } while (0)
; #define PG8_LDB(dst, b, h) do { _Pragma("unroll") for (int n = 0; n < 2; ++n) _Pragma("unroll") for (int k = 0; k < 2; ++k) dst[n][k] = *(const PG8_LAS bf16x8*)(lds + PG8_SB(b, h) + boff + n * 2048 + k * 1024); } while (0)
; #define PG8_MMA(ai, bj, At, Bt) do { __builtin_amdgcn_s_setprio(1); _Pragma("unroll") for (int m = 0; m < 4; ++m) _Pragma("unroll") for (int n = 0; n < 2; ++n) _Pragma("unroll") for (int k = 0; k < 2; ++k) \
;         acc[ai][bj][m][n] = __builtin_amdgcn_mfma_f32_16x16x32_bf16(Bt[n][k], At[m][k], acc[ai][bj][m][n], 0, 0, 0); __builtin_amdgcn_s_setprio(0); } while (0)
; #define PG8_WAIT_V(n) asm volatile("s_waitcnt vmcnt(" #n ")" ::: "memory")
; #define PG8_WAIT_L(n) asm volatile("s_waitcnt lgkmcnt(" #n ")" ::: "memory")
; #define PG8_BAR __builtin_amdgcn_s_barrier()
; #define PG8_SCHED __builtin_amdgcn_sched_barrier(0)
; template <class Epi, class Sched>
; __device__ __forceinline__ void gemm_phase(PG8_LAS unsigned char* lds, const Gemm g, const Sched& S, const Epi& E) {
;     ...
;             PG8_LDB(B0, 0, 0); PG8_SCHED; PG8_LDA(At, 0, 0); PG8_STAGE(PG8_SA(1, 1), a1 + hstep, voffA);
;             PG8_WAIT_L(8); PG8_BAR; PG8_WAIT_L(0); PG8_MMA(0, 0, At, B0); PG8_BAR; PG8_SCHED;
;             PG8_LDB(B1, 0, 1); PG8_STAGE(PG8_SB(0, 0), b2, voffB);
;             PG8_BAR; PG8_WAIT_L(0); PG8_MMA(0, 1, At, B1); PG8_BAR;
;             PG8_LDA(At, 0, 1); PG8_STAGE(PG8_SA(0, 0), a2, voffA);
;             PG8_BAR; PG8_WAIT_L(0); PG8_MMA(1, 0, At, B0); PG8_BAR; PG8_SCHED;
;             PG8_STAGE(PG8_SB(0, 1), b2 + hstep, voffB);
;             PG8_WAIT_V(6); PG8_BAR; PG8_MMA(1, 1, At, B1); PG8_BAR;
;     __device__ __forceinline__ void operator()(const AccT& acc, const pg8::Unit& u, int wr, int wc, int fr, int fq) const {
;     ...
;                 const f32x4 l0 = *(const f32x4*)(lb + col), l1 = *(const f32x4*)(lb + col + 4);
.LBB0_234:
	s_ashr_i32 s49, s48, 31
	v_cmp_lt_i64_e32 vcc, s[50:51], v[152:153]
	s_lshl_b64 s[50:51], s[48:49], 20
	s_add_u32 s50, s76, s50
	s_addc_u32 s51, s77, s51
	s_and_b64 s[64:65], vcc, exec
	s_cselect_b32 s0, s51, s69
	s_cselect_b32 s5, s50, s68
	s_ashr_i32 s47, s46, 31
	s_lshl_b64 s[64:65], s[46:47], 20
	s_add_u32 s64, s58, s64
	s_addc_u32 s65, s59, s65
	s_and_b64 s[72:73], vcc, exec
	s_cselect_b32 s47, s65, s71
	s_cselect_b32 s49, s64, s70
	s_add_u32 s68, s68, 0x80080
	s_addc_u32 s69, s69, 0
	s_add_u32 s97, s70, 0x100
	s_addc_u32 vcc_lo, s71, 0
	s_mov_b32 vcc_hi, -2
	v_lshl_or_b32 v244, s66, 8, v146
	v_ashrrev_i32_e32 v245, 31, v244
	v_lshl_add_u64 v[244:245], v[244:245], 2, s[20:21]
	global_load_dwordx4 v[236:239], v[244:245], off
	global_load_dwordx4 v[246:249], v[244:245], off offset:16
	global_load_dwordx4 v[226:229], v[244:245], off offset:512
	global_load_dwordx4 v[230:233], v[244:245], off offset:528
	s_setprio 0
	ds_read_b128 v[128:131], v162
	ds_read_b128 v[132:135], v162 offset:1024
	ds_read_b128 v[154:157], v162 offset:2048
	ds_read_b128 v[166:169], v162 offset:3072
	ds_read_b128 v[170:173], v163
	ds_read_b128 v[174:177], v163 offset:1024
	ds_read_b128 v[178:181], v163 offset:2048
	ds_read_b128 v[182:185], v163 offset:3072
	ds_read_b128 v[186:189], v163 offset:4096
	ds_read_b128 v[190:193], v163 offset:5120
	ds_read_b128 v[194:197], v163 offset:6144
	ds_read_b128 v[198:201], v163 offset:7168
	s_waitcnt lgkmcnt(11)
	ds_read_b128 v[202:205], v164
	ds_read_b128 v[206:209], v164 offset:1024
	ds_read_b128 v[210:213], v164 offset:2048
	ds_read_b128 v[214:217], v164 offset:3072
	s_add_u32 s10, s68, 0xfff80080
	s_addc_u32 s11, s69, -1
	s_cmp_eq_u32 vcc_hi, 28
	s_cselect_b32 s73, s0, s11
	s_cselect_b32 s72, s5, s10
	s_cselect_b32 s71, s47, vcc_lo
	s_cselect_b32 s70, s49, s97
	s_add_u32 s98, s70, s26
	s_addc_u32 s99, s71, s27
	s_add_u32 s100, s72, s26
	s_addc_u32 s101, s73, s27
	s_add_i32 m0, s67, 0xc000
	s_nop 0
	global_load_lds_dwordx4 v148, s[68:69]
	s_add_i32 m0, s67, 0xe000
	s_nop 0
	global_load_lds_dwordx4 v150, s[68:69]
	s_waitcnt vmcnt(8)
	s_waitcnt lgkmcnt(0)
	s_setprio 1
	s_barrier
	v_mfma_f32_16x16x32_bf16 v[124:127], v[128:131], v[170:173], 0
	v_mfma_f32_16x16x32_bf16 v[120:123], v[154:157], v[170:173], 0
	v_mfma_f32_16x16x32_bf16 v[116:119], v[128:131], v[178:181], 0
	v_mfma_f32_16x16x32_bf16 v[112:115], v[154:157], v[178:181], 0
	v_mfma_f32_16x16x32_bf16 v[108:111], v[128:131], v[186:189], 0
	v_mfma_f32_16x16x32_bf16 v[104:107], v[154:157], v[186:189], 0
	v_mfma_f32_16x16x32_bf16 v[100:103], v[128:131], v[194:197], 0
	v_mfma_f32_16x16x32_bf16 v[96:99], v[154:157], v[194:197], 0
	v_mfma_f32_16x16x32_bf16 v[124:127], v[132:135], v[174:177], v[124:127]
	v_mfma_f32_16x16x32_bf16 v[120:123], v[166:169], v[174:177], v[120:123]
	v_mfma_f32_16x16x32_bf16 v[116:119], v[132:135], v[182:185], v[116:119]
	v_mfma_f32_16x16x32_bf16 v[112:115], v[166:169], v[182:185], v[112:115]
	v_mfma_f32_16x16x32_bf16 v[108:111], v[132:135], v[190:193], v[108:111]
	v_mfma_f32_16x16x32_bf16 v[104:107], v[166:169], v[190:193], v[104:107]
	v_mfma_f32_16x16x32_bf16 v[100:103], v[132:135], v[198:201], v[100:103]
	v_mfma_f32_16x16x32_bf16 v[96:99], v[166:169], v[198:201], v[96:99]
	v_mfma_f32_16x16x32_bf16 v[60:63], v[202:205], v[170:173], 0
	v_mfma_f32_16x16x32_bf16 v[56:59], v[210:213], v[170:173], 0
	v_mfma_f32_16x16x32_bf16 v[52:55], v[202:205], v[178:181], 0
	v_mfma_f32_16x16x32_bf16 v[48:51], v[210:213], v[178:181], 0
	v_mfma_f32_16x16x32_bf16 v[44:47], v[202:205], v[186:189], 0
	v_mfma_f32_16x16x32_bf16 v[40:43], v[210:213], v[186:189], 0
	v_mfma_f32_16x16x32_bf16 v[36:39], v[202:205], v[194:197], 0
	v_mfma_f32_16x16x32_bf16 v[32:35], v[210:213], v[194:197], 0
	v_mfma_f32_16x16x32_bf16 v[60:63], v[206:209], v[174:177], v[60:63]
	v_mfma_f32_16x16x32_bf16 v[56:59], v[214:217], v[174:177], v[56:59]
	v_mfma_f32_16x16x32_bf16 v[52:55], v[206:209], v[182:185], v[52:55]
	v_mfma_f32_16x16x32_bf16 v[48:51], v[214:217], v[182:185], v[48:51]
	v_mfma_f32_16x16x32_bf16 v[44:47], v[206:209], v[190:193], v[44:47]
	v_mfma_f32_16x16x32_bf16 v[40:43], v[214:217], v[190:193], v[40:43]
	v_mfma_f32_16x16x32_bf16 v[36:39], v[206:209], v[198:201], v[36:39]
	v_mfma_f32_16x16x32_bf16 v[32:35], v[214:217], v[198:201], v[32:35]
	s_barrier
	s_setprio 0
	ds_read_b128 v[170:173], v163 offset:16384
	ds_read_b128 v[174:177], v163 offset:17408
	ds_read_b128 v[178:181], v163 offset:18432
	ds_read_b128 v[182:185], v163 offset:19456
	ds_read_b128 v[186:189], v163 offset:20480
	ds_read_b128 v[190:193], v163 offset:21504
	ds_read_b128 v[194:197], v163 offset:22528
	ds_read_b128 v[198:201], v163 offset:23552
	s_add_i32 s10, s90, s78
	s_mov_b32 m0, s10
	s_nop 0
	global_load_lds_dwordx4 v138, s[70:71]
	s_add_i32 m0, s10, 0x2000
	s_nop 0
	global_load_lds_dwordx4 v142, s[70:71]
	s_mov_b32 m0, s67
	s_nop 0
	global_load_lds_dwordx4 v136, s[72:73]
	s_mov_b32 m0, s79
	s_nop 0
	global_load_lds_dwordx4 v140, s[72:73]
	s_add_u32 s10, s70, 0x80000
	s_addc_u32 s11, s71, 0
	s_add_i32 s33, s91, s78
	s_mov_b32 m0, s33
	s_nop 0
	global_load_lds_dwordx4 v138, s[10:11]
	s_add_i32 m0, s33, 0x2000
	s_nop 0
	global_load_lds_dwordx4 v142, s[10:11]
	s_waitcnt vmcnt(8)
	s_waitcnt lgkmcnt(0)
	s_setprio 1
	s_barrier
; #define PG8_STAGE(bufoff, gbase, voff) do { _Pragma("unroll") for (int _i = 0; _i < 2; ++_i) \
;         __builtin_amdgcn_global_load_lds((const unsigned*)((const char*)(gbase) + (voff)[_i]), (PG8_LAS unsigned*)(lds + (bufoff) + ldsw + _i * 8192), 16, 0, 0); } while (0)
; #define PG8_LDA(dst, b, h) do { _Pragma("unroll") for (int m = 0; m < 4; ++m) _Pragma("unroll") for (int k = 0; k < 2; ++k) dst[m][k] = *(const PG8_LAS bf16x8*)(lds + PG8_SA(b, h) + aoff + m * 2048 + k * 1024); } while (0)
; #define PG8_LDB(dst, b, h) do { _Pragma("unroll") for (int n = 0; n < 2; ++n) _Pragma("unroll") for (int k = 0; k < 2; ++k) dst[n][k] = *(const PG8_LAS bf16x8*)(lds + PG8_SB(b, h) + boff + n * 2048 + k * 1024); } while (0)
; #define PG8_MMA(ai, bj, At, Bt) do { __builtin_amdgcn_s_setprio(1); _Pragma("unroll") for (int m = 0; m < 4; ++m) _Pragma("unroll") for (int n = 0; n < 2; ++n) _Pragma("unroll") for (int k = 0; k < 2; ++k) \
;         acc[ai][bj][m][n] = __builtin_amdgcn_mfma_f32_16x16x32_bf16(Bt[n][k], At[m][k], acc[ai][bj][m][n], 0, 0, 0); __builtin_amdgcn_s_setprio(0); } while (0)
; #define PG8_WAIT_V(n) asm volatile("s_waitcnt vmcnt(" #n ")" ::: "memory")
; #define PG8_WAIT_L(n) asm volatile("s_waitcnt lgkmcnt(" #n ")" ::: "memory")
; #define PG8_BAR __builtin_amdgcn_s_barrier()
; #define PG8_SCHED __builtin_amdgcn_sched_barrier(0)
; template <class Epi, class Sched>
; __device__ __forceinline__ void gemm_phase(PG8_LAS unsigned char* lds, const Gemm g, const Sched& S, const Epi& E) {
;     ...
;             PG8_BAR; PG8_WAIT_L(0); PG8_MMA(0, 1, At, B1); PG8_BAR;
;             PG8_LDA(At, 0, 1); PG8_STAGE(PG8_SA(0, 0), a2, voffA);
;             PG8_BAR; PG8_WAIT_L(0); PG8_MMA(1, 0, At, B0); PG8_BAR; PG8_SCHED;
;             PG8_STAGE(PG8_SB(0, 1), b2 + hstep, voffB);
;             PG8_WAIT_V(6); PG8_BAR; PG8_MMA(1, 1, At, B1); PG8_BAR;
;             PG8_LDB(B0, 1, 0); PG8_SCHED; PG8_LDA(At, 1, 0); PG8_STAGE(PG8_SA(0, 1), a2 + hstep, voffA);
;             PG8_WAIT_L(8); PG8_BAR; PG8_WAIT_L(0); PG8_MMA(0, 0, At, B0); PG8_BAR; PG8_SCHED;
;             PG8_LDB(B1, 1, 1); PG8_STAGE(PG8_SB(1, 0), b3, voffB);
;             PG8_BAR; PG8_WAIT_L(0); PG8_MMA(0, 1, At, B1); PG8_BAR;
	v_mfma_f32_16x16x32_bf16 v[92:95], v[128:131], v[170:173], 0
	v_mfma_f32_16x16x32_bf16 v[88:91], v[154:157], v[170:173], 0
	v_mfma_f32_16x16x32_bf16 v[84:87], v[128:131], v[178:181], 0
	v_mfma_f32_16x16x32_bf16 v[80:83], v[154:157], v[178:181], 0
	v_mfma_f32_16x16x32_bf16 v[76:79], v[128:131], v[186:189], 0
	v_mfma_f32_16x16x32_bf16 v[72:75], v[154:157], v[186:189], 0
	v_mfma_f32_16x16x32_bf16 v[68:71], v[128:131], v[194:197], 0
	v_mfma_f32_16x16x32_bf16 v[64:67], v[154:157], v[194:197], 0
	s_add_i32 s33, 0, 0x18000
	v_add_u32_e32 v144, s33, v160
	v_mfma_f32_16x16x32_bf16 v[92:95], v[132:135], v[174:177], v[92:95]
	v_mfma_f32_16x16x32_bf16 v[88:91], v[166:169], v[174:177], v[88:91]
	v_mfma_f32_16x16x32_bf16 v[84:87], v[132:135], v[182:185], v[84:87]
	v_mfma_f32_16x16x32_bf16 v[80:83], v[166:169], v[182:185], v[80:83]
	v_mfma_f32_16x16x32_bf16 v[76:79], v[132:135], v[190:193], v[76:79]
	v_mfma_f32_16x16x32_bf16 v[72:75], v[166:169], v[190:193], v[72:75]
	v_mfma_f32_16x16x32_bf16 v[68:71], v[132:135], v[198:201], v[68:71]
	v_mfma_f32_16x16x32_bf16 v[64:67], v[166:169], v[198:201], v[64:67]
	v_mfma_f32_16x16x32_bf16 v[28:31], v[202:205], v[170:173], 0
	v_mfma_f32_16x16x32_bf16 v[24:27], v[210:213], v[170:173], 0
	v_mfma_f32_16x16x32_bf16 v[20:23], v[202:205], v[178:181], 0
	v_mfma_f32_16x16x32_bf16 v[16:19], v[210:213], v[178:181], 0
	v_mfma_f32_16x16x32_bf16 v[12:15], v[202:205], v[186:189], 0
	v_mfma_f32_16x16x32_bf16 v[8:11], v[210:213], v[186:189], 0
	v_mfma_f32_16x16x32_bf16 v[4:7], v[202:205], v[194:197], 0
	v_mfma_f32_16x16x32_bf16 v[0:3], v[210:213], v[194:197], 0
	v_mfma_f32_16x16x32_bf16 v[28:31], v[206:209], v[174:177], v[28:31]
	v_mfma_f32_16x16x32_bf16 v[24:27], v[214:217], v[174:177], v[24:27]
	v_mfma_f32_16x16x32_bf16 v[20:23], v[206:209], v[182:185], v[20:23]
	v_mfma_f32_16x16x32_bf16 v[16:19], v[214:217], v[182:185], v[16:19]
	v_mfma_f32_16x16x32_bf16 v[12:15], v[206:209], v[190:193], v[12:15]
	v_mfma_f32_16x16x32_bf16 v[8:11], v[214:217], v[190:193], v[8:11]
	v_mfma_f32_16x16x32_bf16 v[4:7], v[206:209], v[198:201], v[4:7]
	v_mfma_f32_16x16x32_bf16 v[0:3], v[214:217], v[198:201], v[0:3]
	s_barrier
	s_setprio 0
	ds_read_b128 v[128:131], v162 offset:32768
	ds_read_b128 v[132:135], v162 offset:33792
	ds_read_b128 v[154:157], v162 offset:34816
	ds_read_b128 v[166:169], v162 offset:35840
	ds_read_b128 v[170:173], v163 offset:32768
	ds_read_b128 v[174:177], v163 offset:33792
	ds_read_b128 v[178:181], v163 offset:34816
	ds_read_b128 v[182:185], v163 offset:35840
	ds_read_b128 v[186:189], v163 offset:36864
	ds_read_b128 v[190:193], v163 offset:37888
	ds_read_b128 v[194:197], v163 offset:38912
	ds_read_b128 v[198:201], v163 offset:39936
	s_waitcnt lgkmcnt(11)
	ds_read_b128 v[202:205], v164 offset:32768
	ds_read_b128 v[206:209], v164 offset:33792
	ds_read_b128 v[210:213], v164 offset:34816
	ds_read_b128 v[214:217], v164 offset:35840
	s_add_u32 s10, s72, 0x80000
	s_addc_u32 s11, s73, 0
	s_mov_b32 m0, s80
	s_nop 0
	global_load_lds_dwordx4 v136, s[10:11]
	s_mov_b32 m0, s81
	s_nop 0
	global_load_lds_dwordx4 v140, s[10:11]
	s_waitcnt vmcnt(8)
	s_waitcnt lgkmcnt(0)
	s_setprio 1
	s_barrier
	v_mfma_f32_16x16x32_bf16 v[124:127], v[128:131], v[170:173], v[124:127]
	v_mfma_f32_16x16x32_bf16 v[120:123], v[154:157], v[170:173], v[120:123]
	v_mfma_f32_16x16x32_bf16 v[116:119], v[128:131], v[178:181], v[116:119]
	v_mfma_f32_16x16x32_bf16 v[112:115], v[154:157], v[178:181], v[112:115]
	v_mfma_f32_16x16x32_bf16 v[108:111], v[128:131], v[186:189], v[108:111]
	v_mfma_f32_16x16x32_bf16 v[104:107], v[154:157], v[186:189], v[104:107]
	v_mfma_f32_16x16x32_bf16 v[100:103], v[128:131], v[194:197], v[100:103]
	v_mfma_f32_16x16x32_bf16 v[96:99], v[154:157], v[194:197], v[96:99]
	v_mfma_f32_16x16x32_bf16 v[124:127], v[132:135], v[174:177], v[124:127]
	v_mfma_f32_16x16x32_bf16 v[120:123], v[166:169], v[174:177], v[120:123]
	v_mfma_f32_16x16x32_bf16 v[116:119], v[132:135], v[182:185], v[116:119]
	v_mfma_f32_16x16x32_bf16 v[112:115], v[166:169], v[182:185], v[112:115]
	v_mfma_f32_16x16x32_bf16 v[108:111], v[132:135], v[190:193], v[108:111]
	v_mfma_f32_16x16x32_bf16 v[104:107], v[166:169], v[190:193], v[104:107]
	v_mfma_f32_16x16x32_bf16 v[100:103], v[132:135], v[198:201], v[100:103]
	v_mfma_f32_16x16x32_bf16 v[96:99], v[166:169], v[198:201], v[96:99]
	v_mfma_f32_16x16x32_bf16 v[60:63], v[202:205], v[170:173], v[60:63]
	v_mfma_f32_16x16x32_bf16 v[56:59], v[210:213], v[170:173], v[56:59]
	v_mfma_f32_16x16x32_bf16 v[52:55], v[202:205], v[178:181], v[52:55]
	v_mfma_f32_16x16x32_bf16 v[48:51], v[210:213], v[178:181], v[48:51]
	v_mfma_f32_16x16x32_bf16 v[44:47], v[202:205], v[186:189], v[44:47]
	v_mfma_f32_16x16x32_bf16 v[40:43], v[210:213], v[186:189], v[40:43]
	v_mfma_f32_16x16x32_bf16 v[36:39], v[202:205], v[194:197], v[36:39]
	v_mfma_f32_16x16x32_bf16 v[32:35], v[210:213], v[194:197], v[32:35]
	v_mfma_f32_16x16x32_bf16 v[60:63], v[206:209], v[174:177], v[60:63]
	v_mfma_f32_16x16x32_bf16 v[56:59], v[214:217], v[174:177], v[56:59]
	v_mfma_f32_16x16x32_bf16 v[52:55], v[206:209], v[182:185], v[52:55]
	v_mfma_f32_16x16x32_bf16 v[48:51], v[214:217], v[182:185], v[48:51]
	v_mfma_f32_16x16x32_bf16 v[44:47], v[206:209], v[190:193], v[44:47]
	v_mfma_f32_16x16x32_bf16 v[40:43], v[214:217], v[190:193], v[40:43]
	v_mfma_f32_16x16x32_bf16 v[36:39], v[206:209], v[198:201], v[36:39]
	v_mfma_f32_16x16x32_bf16 v[32:35], v[214:217], v[198:201], v[32:35]
	s_barrier
; #define PG8_STAGE(bufoff, gbase, voff) do { _Pragma("unroll") for (int _i = 0; _i < 2; ++_i) \
;         __builtin_amdgcn_global_load_lds((const unsigned*)((const char*)(gbase) + (voff)[_i]), (PG8_LAS unsigned*)(lds + (bufoff) + ldsw + _i * 8192), 16, 0, 0); } while (0)
; #define PG8_LDA(dst, b, h) do { _Pragma("unroll") for (int m = 0; m < 4; ++m) _Pragma("unroll") for (int k = 0; k < 2; ++k) dst[m][k] = *(const PG8_LAS bf16x8*)(lds + PG8_SA(b, h) + aoff + m * 2048 + k * 1024); } while (0)
; #define PG8_LDB(dst, b, h) do { _Pragma("unroll") for (int n = 0; n < 2; ++n) _Pragma("unroll") for (int k = 0; k < 2; ++k) dst[n][k] = *(const PG8_LAS bf16x8*)(lds + PG8_SB(b, h) + boff + n * 2048 + k * 1024); } while (0)
; #define PG8_MMA(ai, bj, At, Bt) do { __builtin_amdgcn_s_setprio(1); _Pragma("unroll") for (int m = 0; m < 4; ++m) _Pragma("unroll") for (int n = 0; n < 2; ++n) _Pragma("unroll") for (int k = 0; k < 2; ++k) \
;         acc[ai][bj][m][n] = __builtin_amdgcn_mfma_f32_16x16x32_bf16(Bt[n][k], At[m][k], acc[ai][bj][m][n], 0, 0, 0); __builtin_amdgcn_s_setprio(0); } while (0)
; #define PG8_WAIT_V(n) asm volatile("s_waitcnt vmcnt(" #n ")" ::: "memory")
; #define PG8_WAIT_L(n) asm volatile("s_waitcnt lgkmcnt(" #n ")" ::: "memory")
; #define PG8_BAR __builtin_amdgcn_s_barrier()
; #define PG8_SCHED __builtin_amdgcn_sched_barrier(0)
; template <class Epi, class Sched>
; __device__ __forceinline__ void gemm_phase(PG8_LAS unsigned char* lds, const Gemm g, const Sched& S, const Epi& E) {
;     ...
;             PG8_LDB(B1, 1, 1); PG8_STAGE(PG8_SB(1, 0), b3, voffB);
;             PG8_BAR; PG8_WAIT_L(0); PG8_MMA(0, 1, At, B1); PG8_BAR;
;             PG8_LDA(At, 1, 1); PG8_STAGE(PG8_SA(1, 0), a3, voffA);
;             PG8_BAR; PG8_WAIT_L(0); PG8_MMA(1, 0, At, B0); PG8_BAR; PG8_SCHED;
;             PG8_STAGE(PG8_SB(1, 1), b3 + hstep, voffB);
;             PG8_WAIT_V(6); PG8_BAR; PG8_MMA(1, 1, At, B1); PG8_BAR;
	s_setprio 0
	ds_read_b128 v[170:173], v163 offset:49152
	ds_read_b128 v[174:177], v163 offset:50176
	ds_read_b128 v[178:181], v163 offset:51200
	ds_read_b128 v[182:185], v163 offset:52224
	ds_read_b128 v[186:189], v163 offset:53248
	ds_read_b128 v[190:193], v163 offset:54272
	ds_read_b128 v[194:197], v163 offset:55296
	ds_read_b128 v[198:201], v163 offset:56320
	s_add_i32 s72, 0, 0x1c000
	s_add_i32 s10, s33, s78
	v_add_u32_e32 v144, s72, v160
	s_mov_b32 m0, s10
	s_nop 0
	global_load_lds_dwordx4 v138, s[98:99]
	s_add_i32 m0, s10, 0x2000
	s_nop 0
	global_load_lds_dwordx4 v142, s[98:99]
	s_mov_b32 m0, s84
	s_nop 0
	global_load_lds_dwordx4 v136, s[100:101]
	s_mov_b32 m0, s85
	s_nop 0
	global_load_lds_dwordx4 v140, s[100:101]
	s_add_u32 s10, s70, 0x80080
	s_addc_u32 s11, s71, 0
	s_add_i32 s33, s72, s78
	s_mov_b32 m0, s33
	s_nop 0
	global_load_lds_dwordx4 v138, s[10:11]
	s_add_i32 m0, s33, 0x2000
	s_nop 0
	global_load_lds_dwordx4 v142, s[10:11]
	s_waitcnt vmcnt(8)
	s_waitcnt lgkmcnt(0)
	s_setprio 1
	s_barrier
	v_mfma_f32_16x16x32_bf16 v[92:95], v[128:131], v[170:173], v[92:95]
	v_mfma_f32_16x16x32_bf16 v[88:91], v[154:157], v[170:173], v[88:91]
	v_mfma_f32_16x16x32_bf16 v[84:87], v[128:131], v[178:181], v[84:87]
	v_mfma_f32_16x16x32_bf16 v[80:83], v[154:157], v[178:181], v[80:83]
	v_mfma_f32_16x16x32_bf16 v[76:79], v[128:131], v[186:189], v[76:79]
	v_mfma_f32_16x16x32_bf16 v[72:75], v[154:157], v[186:189], v[72:75]
	v_mfma_f32_16x16x32_bf16 v[68:71], v[128:131], v[194:197], v[68:71]
	v_mfma_f32_16x16x32_bf16 v[64:67], v[154:157], v[194:197], v[64:67]
	s_add_i32 vcc_hi, vcc_hi, 2
	s_add_u32 s68, s68, 0x100
	s_addc_u32 s69, s69, 0
	s_add_u32 s97, s97, 0x100
	s_addc_u32 vcc_lo, vcc_lo, 0
	s_cmp_gt_u32 vcc_hi, 29
	v_mfma_f32_16x16x32_bf16 v[92:95], v[132:135], v[174:177], v[92:95]
	v_mfma_f32_16x16x32_bf16 v[88:91], v[166:169], v[174:177], v[88:91]
	v_mfma_f32_16x16x32_bf16 v[84:87], v[132:135], v[182:185], v[84:87]
	v_mfma_f32_16x16x32_bf16 v[80:83], v[166:169], v[182:185], v[80:83]
	v_mfma_f32_16x16x32_bf16 v[76:79], v[132:135], v[190:193], v[76:79]
	v_mfma_f32_16x16x32_bf16 v[72:75], v[166:169], v[190:193], v[72:75]
	v_mfma_f32_16x16x32_bf16 v[68:71], v[132:135], v[198:201], v[68:71]
	v_mfma_f32_16x16x32_bf16 v[64:67], v[166:169], v[198:201], v[64:67]
	v_mfma_f32_16x16x32_bf16 v[28:31], v[202:205], v[170:173], v[28:31]
	v_mfma_f32_16x16x32_bf16 v[24:27], v[210:213], v[170:173], v[24:27]
	v_mfma_f32_16x16x32_bf16 v[20:23], v[202:205], v[178:181], v[20:23]
	v_mfma_f32_16x16x32_bf16 v[16:19], v[210:213], v[178:181], v[16:19]
	v_mfma_f32_16x16x32_bf16 v[12:15], v[202:205], v[186:189], v[12:15]
	v_mfma_f32_16x16x32_bf16 v[8:11], v[210:213], v[186:189], v[8:11]
	v_mfma_f32_16x16x32_bf16 v[4:7], v[202:205], v[194:197], v[4:7]
	v_mfma_f32_16x16x32_bf16 v[0:3], v[210:213], v[194:197], v[0:3]
	v_mfma_f32_16x16x32_bf16 v[28:31], v[206:209], v[174:177], v[28:31]
	v_mfma_f32_16x16x32_bf16 v[24:27], v[214:217], v[174:177], v[24:27]
	v_mfma_f32_16x16x32_bf16 v[20:23], v[206:209], v[182:185], v[20:23]
	v_mfma_f32_16x16x32_bf16 v[16:19], v[214:217], v[182:185], v[16:19]
	v_mfma_f32_16x16x32_bf16 v[12:15], v[206:209], v[190:193], v[12:15]
	v_mfma_f32_16x16x32_bf16 v[8:11], v[214:217], v[190:193], v[8:11]
	v_mfma_f32_16x16x32_bf16 v[4:7], v[206:209], v[198:201], v[4:7]
	v_mfma_f32_16x16x32_bf16 v[0:3], v[214:217], v[198:201], v[0:3]
	s_barrier

;     __device__ __forceinline__ void operator()(const AccT& acc, const pg8::Unit& u, int wr, int wc, int fr, int fq) const {
;     ...
;         if (pn < 8) {
; #pragma unroll
;             for (int bj = 0; bj < 2; ++bj) {
;                 const int col = pn * 256 + bj * 128 + cl;
;                 const f32x4 l0 = *(const f32x4*)(lb + col), l1 = *(const f32x4*)(lb + col + 4);
; #pragma unroll
;                 for (int ai = 0; ai < 2; ++ai)
; #pragma unroll
;                     for (int m = 0; m < 4; ++m) {
;                         const f32x4 a = acc[ai][bj][m][0], b = acc[ai][bj][m][1]; float g[8];
; #pragma unroll
;                         for (int j = 0; j < 4; ++j) { g[j] = (1.f - l0[j]) * __builtin_amdgcn_rcpf(1.f + __expf(a[j])); g[4 + j] = (1.f - l1[j]) * __builtin_amdgcn_rcpf(1.f + __expf(b[j])); }
;                         u32x4 w; w.x = pk_h2(g[0], g[1]); w.y = pk_h2(g[2], g[3]); w.z = pk_h2(g[4], g[5]); w.w = pk_h2(g[6], g[7]);
;                         *(u32x4*)(G + (size_t)(row0 + ai * 128 + m * 16) * 2048 + col) = w;
;                     }
.LBB0_277:
	s_andn2_b64 vcc, exec, s[68:69]
	s_cbranch_vccnz .LBB0_231
	v_lshl_or_b32 v128, s66, 8, v146
	v_ashrrev_i32_e32 v129, 31, v128
	v_lshl_add_u64 v[134:135], v[128:129], 2, s[20:21]
	s_nop 0
	s_nop 0
	s_nop 0
	s_nop 0
	v_mul_f32_e32 v124, 0x3fb8aa3b, v124
	v_mul_f32_e32 v120, 0x3fb8aa3b, v120
	v_mul_f32_e32 v125, 0x3fb8aa3b, v125
	v_mul_f32_e32 v121, 0x3fb8aa3b, v121
	v_ashrrev_i32_e32 v155, 31, v154
	v_mul_f32_e32 v134, 0x3fb8aa3b, v112
	v_mul_f32_e32 v135, 0x3fb8aa3b, v113
	v_mul_f32_e32 v114, 0x3fb8aa3b, v114
	v_exp_f32_e32 v124, v124
	v_exp_f32_e32 v120, v120
	v_exp_f32_e32 v125, v125
	v_exp_f32_e32 v121, v121
	v_lshlrev_b64 v[112:113], 12, v[154:155]
	v_exp_f32_e32 v144, v134
	v_exp_f32_e32 v155, v135
	v_exp_f32_e32 v114, v114
	v_mul_f32_e32 v122, 0x3fb8aa3b, v122
	v_mul_f32_e32 v123, 0x3fb8aa3b, v123
	v_mul_f32_e32 v126, 0x3fb8aa3b, v126
	v_mul_f32_e32 v127, 0x3fb8aa3b, v127
	v_mul_f32_e32 v119, 0x3fb8aa3b, v119
	v_mul_f32_e32 v115, 0x3fb8aa3b, v115
	v_exp_f32_e32 v122, v122
	v_exp_f32_e32 v123, v123
	v_exp_f32_e32 v126, v126
	v_exp_f32_e32 v127, v127
	v_exp_f32_e32 v165, v119
	v_exp_f32_e32 v168, v115
	v_add_f32_e32 v115, 1.0, v124
	v_add_f32_e32 v119, 1.0, v120
	v_add_f32_e32 v120, 1.0, v125
	v_mul_f32_e32 v118, 0x3fb8aa3b, v118
	v_lshlrev_b64 v[134:135], 1, v[128:129]
	v_add_f32_e32 v121, 1.0, v121
	v_add_f32_e32 v129, 1.0, v144
	v_add_f32_e32 v144, 1.0, v155
	v_add_f32_e32 v155, 1.0, v114
	v_rcp_f32_e32 v114, v115
	v_rcp_f32_e32 v115, v120
	v_mul_f32_e32 v116, 0x3fb8aa3b, v116
	v_mul_f32_e32 v117, 0x3fb8aa3b, v117
	v_exp_f32_e32 v118, v118
	v_rcp_f32_e32 v124, v119
	v_rcp_f32_e32 v125, v121
	v_exp_f32_e32 v116, v116
	v_exp_f32_e32 v117, v117
	v_add_f32_e32 v122, 1.0, v122
	v_add_f32_e32 v123, 1.0, v123
	v_add_f32_e32 v126, 1.0, v126
	v_add_f32_e32 v127, 1.0, v127
	v_rcp_f32_e32 v166, v122
	v_rcp_f32_e32 v167, v123
	v_rcp_f32_e32 v126, v126
	v_rcp_f32_e32 v127, v127
	v_add_f32_e32 v118, 1.0, v118
	v_mul_f32_e32 v108, 0x3fb8aa3b, v108
	v_mul_f32_e32 v104, 0x3fb8aa3b, v104
	v_mul_f32_e32 v109, 0x3fb8aa3b, v109
	v_mul_f32_e32 v105, 0x3fb8aa3b, v105
	v_add_f32_e32 v116, 1.0, v116
	v_add_f32_e32 v117, 1.0, v117
	v_rcp_f32_e32 v171, v118
	v_exp_f32_e32 v108, v108
	v_exp_f32_e32 v104, v104
	v_exp_f32_e32 v109, v109
	v_exp_f32_e32 v105, v105
	v_mul_f32_e32 v106, 0x3fb8aa3b, v106
	v_rcp_f32_e32 v169, v116
	v_rcp_f32_e32 v170, v117
	v_rcp_f32_e32 v155, v155
	v_exp_f32_e32 v106, v106
	v_lshl_add_u64 v[112:113], s[6:7], 0, v[112:113]
	v_lshl_add_u64 v[112:113], v[112:113], 0, v[134:135]
	v_mul_f32_e32 v110, 0x3fb8aa3b, v110
	v_mul_f32_e32 v111, 0x3fb8aa3b, v111
	v_mul_f32_e32 v107, 0x3fb8aa3b, v107
	v_rcp_f32_e32 v129, v129
	v_rcp_f32_e32 v144, v144
	s_nop 0
	v_pk_add_f32 v[122:123], v[236:237], 1.0 op_sel_hi:[1,0] neg_lo:[1,0] neg_hi:[1,0]
	v_pk_add_f32 v[120:121], v[246:247], 1.0 op_sel_hi:[1,0] neg_lo:[1,0] neg_hi:[1,0]
	v_pk_mul_f32 v[114:115], v[114:115], v[122:123]
	v_pk_mul_f32 v[130:131], v[124:125], v[120:121]
	v_cvt_pk_f16_f32 v124, v114, v115
	v_add_f32_e32 v114, 1.0, v165
	v_rcp_f32_e32 v114, v114
	v_add_f32_e32 v115, 1.0, v168
	v_pk_add_f32 v[116:117], v[238:239], 1.0 op_sel_hi:[1,0] neg_lo:[1,0] neg_hi:[1,0]
	v_pk_add_f32 v[118:119], v[248:249], 1.0 op_sel_hi:[1,0] neg_lo:[1,0] neg_hi:[1,0]
	v_rcp_f32_e32 v115, v115
	v_pk_mul_f32 v[126:127], v[126:127], v[116:117]
	v_pk_mul_f32 v[132:133], v[166:167], v[118:119]
	v_cvt_pk_f16_f32 v125, v126, v127
	v_cvt_pk_f16_f32 v126, v130, v131
	v_cvt_pk_f16_f32 v127, v132, v133
	global_store_dwordx4 v[112:113], v[124:127], off
	v_mul_f32_e32 v114, v114, v117
	v_add_f32_e32 v108, 1.0, v108
	v_mul_f32_e32 v125, v171, v116
	v_add_f32_e32 v104, 1.0, v104
	v_add_f32_e32 v109, 1.0, v109
	v_add_f32_e32 v105, 1.0, v105
	v_exp_f32_e32 v110, v110
	v_exp_f32_e32 v111, v111
	v_exp_f32_e32 v107, v107
	v_mul_f32_e32 v100, 0x3fb8aa3b, v100
	v_mul_f32_e32 v96, 0x3fb8aa3b, v96
	v_mul_f32_e32 v101, 0x3fb8aa3b, v101
	v_mul_f32_e32 v97, 0x3fb8aa3b, v97
	v_mul_f32_e32 v127, v155, v118
	v_mul_f32_e32 v115, v115, v119
	v_cvt_pk_f16_f32 v125, v125, v114
	v_or_b32_e32 v114, 16, v154
	v_rcp_f32_e32 v108, v108
	v_rcp_f32_e32 v104, v104
	v_rcp_f32_e32 v109, v109
	v_rcp_f32_e32 v105, v105
	v_add_f32_e32 v106, 1.0, v106
	v_exp_f32_e32 v100, v100
	v_exp_f32_e32 v96, v96
	v_exp_f32_e32 v101, v101
	v_exp_f32_e32 v97, v97
	v_mul_f32_e32 v98, 0x3fb8aa3b, v98
	v_cvt_pk_f16_f32 v127, v127, v115
	v_ashrrev_i32_e32 v115, 31, v114
	v_rcp_f32_e32 v106, v106
	v_exp_f32_e32 v98, v98
	v_lshlrev_b64 v[114:115], 12, v[114:115]
	v_mul_f32_e32 v156, v169, v122
	v_mul_f32_e32 v129, v129, v120
	v_mul_f32_e32 v157, v170, v123
	v_mul_f32_e32 v144, v144, v121
	v_lshl_add_u64 v[114:115], s[6:7], 0, v[114:115]
	v_add_f32_e32 v110, 1.0, v110
	v_add_f32_e32 v111, 1.0, v111
	v_add_f32_e32 v107, 1.0, v107
	v_mul_f32_e32 v102, 0x3fb8aa3b, v102
	v_mul_f32_e32 v103, 0x3fb8aa3b, v103
	v_mul_f32_e32 v99, 0x3fb8aa3b, v99
	v_cvt_pk_f16_f32 v124, v156, v157
	v_cvt_pk_f16_f32 v126, v129, v144
	v_lshl_add_u64 v[114:115], v[114:115], 0, v[134:135]
	v_mul_f32_e32 v108, v108, v122
	v_mul_f32_e32 v104, v104, v120
	v_mul_f32_e32 v109, v109, v123
	v_mul_f32_e32 v105, v105, v121
	v_rcp_f32_e32 v110, v110
	v_rcp_f32_e32 v111, v111
	v_rcp_f32_e32 v107, v107
	v_add_f32_e32 v100, 1.0, v100
	v_add_f32_e32 v96, 1.0, v96
	v_add_f32_e32 v101, 1.0, v101
	v_add_f32_e32 v97, 1.0, v97
	v_exp_f32_e32 v102, v102
	v_exp_f32_e32 v103, v103
	v_exp_f32_e32 v99, v99
	global_store_dwordx4 v[114:115], v[124:127], off
	v_rcp_f32_e32 v100, v100
	v_rcp_f32_e32 v96, v96
	v_mul_f32_e32 v124, v106, v118
	v_cvt_pk_f16_f32 v106, v108, v109
	v_cvt_pk_f16_f32 v108, v104, v105
;     __device__ __forceinline__ void operator()(const AccT& acc, const pg8::Unit& u, int wr, int wc, int fr, int fq) const {
;     ...
;                     for (int m = 0; m < 4; ++m) {
;                         const f32x4 a = acc[ai][bj][m][0], b = acc[ai][bj][m][1]; float g[8];
; #pragma unroll
;                         for (int j = 0; j < 4; ++j) { g[j] = (1.f - l0[j]) * __builtin_amdgcn_rcpf(1.f + __expf(a[j])); g[4 + j] = (1.f - l1[j]) * __builtin_amdgcn_rcpf(1.f + __expf(b[j])); }
;                         u32x4 w; w.x = pk_h2(g[0], g[1]); w.y = pk_h2(g[2], g[3]); w.z = pk_h2(g[4], g[5]); w.w = pk_h2(g[6], g[7]);
;                         *(u32x4*)(G + (size_t)(row0 + ai * 128 + m * 16) * 2048 + col) = w;
;                     }
	v_or_b32_e32 v104, 32, v154
	v_rcp_f32_e32 v101, v101
	v_rcp_f32_e32 v97, v97
	v_add_f32_e32 v98, 1.0, v98
	v_mul_f32_e32 v88, 0x3fb8aa3b, v88
	v_mul_f32_e32 v93, 0x3fb8aa3b, v93
	v_ashrrev_i32_e32 v105, 31, v104
	v_rcp_f32_e32 v98, v98
	v_exp_f32_e32 v88, v88
	v_exp_f32_e32 v93, v93
	v_lshlrev_b64 v[104:105], 12, v[104:105]
	v_mul_f32_e32 v110, v110, v116
	v_mul_f32_e32 v111, v111, v117
	v_mul_f32_e32 v125, v107, v119
	v_lshl_add_u64 v[104:105], s[6:7], 0, v[104:105]
	v_add_f32_e32 v102, 1.0, v102
	v_add_f32_e32 v103, 1.0, v103
	v_add_f32_e32 v99, 1.0, v99
	v_cvt_pk_f16_f32 v107, v110, v111
	v_cvt_pk_f16_f32 v109, v124, v125
	v_lshl_add_u64 v[104:105], v[104:105], 0, v[134:135]
	v_mul_f32_e32 v100, v100, v122
	v_mul_f32_e32 v96, v96, v120
	v_mul_f32_e32 v101, v101, v123
	v_mul_f32_e32 v97, v97, v121
	v_rcp_f32_e32 v102, v102
	v_rcp_f32_e32 v103, v103
	v_rcp_f32_e32 v99, v99
	global_store_dwordx4 v[104:105], v[106:109], off
	v_add_f32_e32 v88, 1.0, v88
	v_add_f32_e32 v93, 1.0, v93
	v_mul_f32_e32 v106, v98, v118
	v_cvt_pk_f16_f32 v98, v100, v101
	v_cvt_pk_f16_f32 v100, v96, v97
	v_or_b32_e32 v96, 48, v154
	v_mul_f32_e32 v89, 0x3fb8aa3b, v89
	v_ashrrev_i32_e32 v97, 31, v96
	v_rcp_f32_e32 v88, v88
	v_rcp_f32_e32 v93, v93
	v_exp_f32_e32 v89, v89
	v_lshlrev_b64 v[96:97], 12, v[96:97]
	v_mul_f32_e32 v102, v102, v116
	v_mul_f32_e32 v103, v103, v117
	v_mul_f32_e32 v107, v99, v119
	v_lshl_add_u64 v[96:97], s[6:7], 0, v[96:97]
	v_cvt_pk_f16_f32 v99, v102, v103
	v_cvt_pk_f16_f32 v101, v106, v107
	v_lshl_add_u64 v[96:97], v[96:97], 0, v[134:135]
	global_store_dwordx4 v[96:97], v[98:101], off
	v_add_f32_e32 v89, 1.0, v89
	v_rcp_f32_e32 v89, v89
	v_mul_f32_e32 v98, v88, v120
	v_mul_f32_e32 v88, v93, v123
	v_mul_f32_e32 v93, 0x3fb8aa3b, v94
	v_exp_f32_e32 v93, v93
	v_mul_f32_e32 v92, 0x3fb8aa3b, v92
	v_exp_f32_e32 v92, v92
	v_mul_f32_e32 v90, 0x3fb8aa3b, v90
	v_mul_f32_e32 v94, v89, v121
	v_add_f32_e32 v89, 1.0, v93
	v_mul_f32_e32 v93, 0x3fb8aa3b, v95
	v_mul_f32_e32 v91, 0x3fb8aa3b, v91
	v_exp_f32_e32 v90, v90
	v_exp_f32_e32 v93, v93
	v_exp_f32_e32 v91, v91
	v_mul_f32_e32 v80, 0x3fb8aa3b, v80
	v_mul_f32_e32 v85, 0x3fb8aa3b, v85
	v_exp_f32_e32 v80, v80
	v_exp_f32_e32 v85, v85
	v_add_f32_e32 v92, 1.0, v92
	v_rcp_f32_e32 v92, v92
	v_add_f32_e32 v90, 1.0, v90
	v_add_f32_e32 v93, 1.0, v93
	v_add_f32_e32 v91, 1.0, v91
	v_rcp_f32_e32 v89, v89
	v_rcp_f32_e32 v90, v90
	v_rcp_f32_e32 v93, v93
	v_rcp_f32_e32 v91, v91
	v_add_f32_e32 v80, 1.0, v80
	v_add_f32_e32 v85, 1.0, v85
	v_mul_f32_e32 v81, 0x3fb8aa3b, v81
	v_rcp_f32_e32 v80, v80
	v_rcp_f32_e32 v85, v85
	v_exp_f32_e32 v81, v81
	v_mul_f32_e32 v92, v92, v122
	v_mul_f32_e32 v89, v89, v116
	v_mul_f32_e32 v95, v90, v118
	v_mul_f32_e32 v90, v93, v117
	v_mul_f32_e32 v91, v91, v119
	v_cvt_pk_f16_f32 v88, v92, v88
	v_add_co_u32_e32 v92, vcc, s92, v112
	v_cvt_pk_f16_f32 v89, v89, v90
	v_cvt_pk_f16_f32 v90, v98, v94
	v_cvt_pk_f16_f32 v91, v95, v91
	v_addc_co_u32_e32 v93, vcc, 0, v113, vcc
	global_store_dwordx4 v[92:93], v[88:91], off
	v_add_f32_e32 v81, 1.0, v81
	v_rcp_f32_e32 v81, v81
	v_mul_f32_e32 v88, v80, v120
	v_mul_f32_e32 v80, v85, v123
	v_mul_f32_e32 v85, 0x3fb8aa3b, v86
	v_exp_f32_e32 v85, v85
	v_mul_f32_e32 v84, 0x3fb8aa3b, v84
	v_exp_f32_e32 v84, v84
	v_mul_f32_e32 v82, 0x3fb8aa3b, v82
	v_mul_f32_e32 v86, v81, v121
	v_add_f32_e32 v81, 1.0, v85
	v_mul_f32_e32 v85, 0x3fb8aa3b, v87
	v_mul_f32_e32 v83, 0x3fb8aa3b, v83
	v_exp_f32_e32 v82, v82
	v_exp_f32_e32 v85, v85
	v_exp_f32_e32 v83, v83
	v_mul_f32_e32 v72, 0x3fb8aa3b, v72
	v_mul_f32_e32 v77, 0x3fb8aa3b, v77
	v_exp_f32_e32 v72, v72
	v_exp_f32_e32 v77, v77
	v_add_f32_e32 v84, 1.0, v84
	v_rcp_f32_e32 v84, v84
	v_add_f32_e32 v82, 1.0, v82
	v_add_f32_e32 v85, 1.0, v85
	v_add_f32_e32 v83, 1.0, v83
	v_rcp_f32_e32 v81, v81
	v_rcp_f32_e32 v82, v82
	v_rcp_f32_e32 v85, v85
	v_rcp_f32_e32 v83, v83
	v_add_f32_e32 v72, 1.0, v72
	v_add_f32_e32 v77, 1.0, v77
	v_mul_f32_e32 v73, 0x3fb8aa3b, v73
	v_rcp_f32_e32 v72, v72
	v_rcp_f32_e32 v77, v77
	v_exp_f32_e32 v73, v73
	v_mul_f32_e32 v84, v84, v122
	v_mul_f32_e32 v81, v81, v116
	v_mul_f32_e32 v87, v82, v118
	v_mul_f32_e32 v82, v85, v117
	v_mul_f32_e32 v83, v83, v119
	v_cvt_pk_f16_f32 v80, v84, v80
	v_add_co_u32_e32 v84, vcc, s93, v112
	v_cvt_pk_f16_f32 v81, v81, v82
	v_cvt_pk_f16_f32 v82, v88, v86
	v_cvt_pk_f16_f32 v83, v87, v83
	v_addc_co_u32_e32 v85, vcc, 0, v113, vcc
	global_store_dwordx4 v[84:85], v[80:83], off
	v_add_f32_e32 v73, 1.0, v73
	v_rcp_f32_e32 v73, v73
	v_mul_f32_e32 v80, v72, v120
	v_mul_f32_e32 v72, v77, v123
	v_mul_f32_e32 v77, 0x3fb8aa3b, v78
	v_exp_f32_e32 v77, v77
	v_mul_f32_e32 v76, 0x3fb8aa3b, v76
	v_exp_f32_e32 v76, v76
	v_mul_f32_e32 v74, 0x3fb8aa3b, v74
	v_mul_f32_e32 v78, v73, v121
	v_add_f32_e32 v73, 1.0, v77
	v_mul_f32_e32 v77, 0x3fb8aa3b, v79
	v_mul_f32_e32 v75, 0x3fb8aa3b, v75
	v_exp_f32_e32 v74, v74
	v_exp_f32_e32 v77, v77
	v_exp_f32_e32 v75, v75
	v_mul_f32_e32 v64, 0x3fb8aa3b, v64
	v_mul_f32_e32 v69, 0x3fb8aa3b, v69
	v_exp_f32_e32 v64, v64
	v_exp_f32_e32 v69, v69
	v_add_f32_e32 v76, 1.0, v76
	v_rcp_f32_e32 v76, v76
	v_add_f32_e32 v74, 1.0, v74
	v_add_f32_e32 v77, 1.0, v77
	v_add_f32_e32 v75, 1.0, v75
	v_rcp_f32_e32 v73, v73
	v_rcp_f32_e32 v74, v74
	v_rcp_f32_e32 v77, v77
	v_rcp_f32_e32 v75, v75
	v_add_f32_e32 v64, 1.0, v64
	v_add_f32_e32 v69, 1.0, v69
	v_mul_f32_e32 v65, 0x3fb8aa3b, v65
	v_rcp_f32_e32 v64, v64
	v_rcp_f32_e32 v69, v69
	v_exp_f32_e32 v65, v65
	v_mul_f32_e32 v76, v76, v122
	v_mul_f32_e32 v73, v73, v116
	v_mul_f32_e32 v79, v74, v118
	v_mul_f32_e32 v74, v77, v117
	v_mul_f32_e32 v75, v75, v119
	v_cvt_pk_f16_f32 v72, v76, v72
	v_add_co_u32_e32 v76, vcc, s94, v112
	v_cvt_pk_f16_f32 v73, v73, v74
;     __device__ __forceinline__ void operator()(const AccT& acc, const pg8::Unit& u, int wr, int wc, int fr, int fq) const {
;     ...
;                 const f32x4 l0 = *(const f32x4*)(lb + col), l1 = *(const f32x4*)(lb + col + 4);
; #pragma unroll
;                 for (int ai = 0; ai < 2; ++ai)
; #pragma unroll
;                     for (int m = 0; m < 4; ++m) {
;                         const f32x4 a = acc[ai][bj][m][0], b = acc[ai][bj][m][1]; float g[8];
; #pragma unroll
;                         for (int j = 0; j < 4; ++j) { g[j] = (1.f - l0[j]) * __builtin_amdgcn_rcpf(1.f + __expf(a[j])); g[4 + j] = (1.f - l1[j]) * __builtin_amdgcn_rcpf(1.f + __expf(b[j])); }
;                         u32x4 w; w.x = pk_h2(g[0], g[1]); w.y = pk_h2(g[2], g[3]); w.z = pk_h2(g[4], g[5]); w.w = pk_h2(g[6], g[7]);
;                         *(u32x4*)(G + (size_t)(row0 + ai * 128 + m * 16) * 2048 + col) = w;
;                     }
	v_cvt_pk_f16_f32 v74, v80, v78
	v_cvt_pk_f16_f32 v75, v79, v75
	v_addc_co_u32_e32 v77, vcc, 0, v113, vcc
	global_store_dwordx4 v[76:77], v[72:75], off
	v_add_f32_e32 v65, 1.0, v65
	v_rcp_f32_e32 v65, v65
	v_mul_f32_e32 v72, v64, v120
	v_mul_f32_e32 v64, v69, v123
	v_mul_f32_e32 v69, 0x3fb8aa3b, v70
	v_exp_f32_e32 v69, v69
	v_mul_f32_e32 v68, 0x3fb8aa3b, v68
	v_exp_f32_e32 v68, v68
	v_mul_f32_e32 v66, 0x3fb8aa3b, v66
	v_mul_f32_e32 v70, v65, v121
	v_add_f32_e32 v65, 1.0, v69
	v_mul_f32_e32 v69, 0x3fb8aa3b, v71
	v_mul_f32_e32 v67, 0x3fb8aa3b, v67
	v_exp_f32_e32 v66, v66
	v_exp_f32_e32 v69, v69
	v_exp_f32_e32 v67, v67
	v_add_f32_e32 v68, 1.0, v68
	v_rcp_f32_e32 v68, v68
	v_add_f32_e32 v66, 1.0, v66
	v_add_f32_e32 v69, 1.0, v69
	v_add_f32_e32 v67, 1.0, v67
	v_rcp_f32_e32 v65, v65
	v_rcp_f32_e32 v66, v66
	v_rcp_f32_e32 v69, v69
	v_rcp_f32_e32 v67, v67
	v_mul_f32_e32 v68, v68, v122
	v_mul_f32_e32 v65, v65, v116
	v_mul_f32_e32 v71, v66, v118
	v_mul_f32_e32 v66, v69, v117
	v_mul_f32_e32 v67, v67, v119
	v_cvt_pk_f16_f32 v64, v68, v64
	v_add_co_u32_e32 v68, vcc, s95, v112
	v_cvt_pk_f16_f32 v65, v65, v66
	v_cvt_pk_f16_f32 v66, v72, v70
	v_cvt_pk_f16_f32 v67, v71, v67
	v_addc_co_u32_e32 v69, vcc, 0, v113, vcc
	global_store_dwordx4 v[68:69], v[64:67], off
	v_mul_f32_e32 v61, 0x3fb8aa3b, v61
	v_exp_f32_e32 v61, v61
	v_or_b32_e32 v64, 0x80, v128
	v_ashrrev_i32_e32 v65, 31, v64
	v_lshl_add_u64 v[64:65], v[64:65], 2, s[20:21]
	s_nop 0
	s_nop 0
	v_mul_f32_e32 v57, 0x3fb8aa3b, v57
	v_mul_f32_e32 v60, 0x3fb8aa3b, v60
	v_mul_f32_e32 v56, 0x3fb8aa3b, v56
	v_exp_f32_e32 v81, v57
	v_add_f32_e32 v57, 1.0, v61
	v_mul_f32_e32 v61, 0x3fb8aa3b, v62
	v_exp_f32_e32 v60, v60
	v_exp_f32_e32 v80, v56
	v_exp_f32_e32 v61, v61
	v_mul_f32_e32 v58, 0x3fb8aa3b, v58
	v_exp_f32_e32 v62, v58
	v_add_f32_e32 v56, 1.0, v60
	v_add_f32_e32 v60, 1.0, v80
	v_add_f32_e32 v58, 1.0, v61
	v_mul_f32_e32 v61, 0x3fb8aa3b, v63
	v_rcp_f32_e32 v80, v60
	v_add_f32_e32 v60, 1.0, v81
	v_exp_f32_e32 v61, v61
	v_mul_f32_e32 v59, 0x3fb8aa3b, v59
	v_rcp_f32_e32 v81, v60
	v_add_f32_e32 v60, 1.0, v62
	v_exp_f32_e32 v62, v59
	v_rcp_f32_e32 v56, v56
	v_rcp_f32_e32 v57, v57
	v_add_f32_e32 v59, 1.0, v61
	v_mul_f32_e32 v48, 0x3fb8aa3b, v48
	v_mul_f32_e32 v53, 0x3fb8aa3b, v53
	v_rcp_f32_e32 v58, v58
	v_rcp_f32_e32 v82, v60
	v_rcp_f32_e32 v59, v59
	v_add_f32_e32 v60, 1.0, v62
	v_exp_f32_e32 v48, v48
	v_exp_f32_e32 v53, v53
	v_rcp_f32_e32 v83, v60
	v_mul_f32_e32 v49, 0x3fb8aa3b, v49
	v_add_f32_e32 v48, 1.0, v48
	v_add_f32_e32 v53, 1.0, v53
	v_rcp_f32_e32 v48, v48
	v_rcp_f32_e32 v53, v53
	v_exp_f32_e32 v49, v49
	v_mul_f32_e32 v52, 0x3fb8aa3b, v52
	v_mul_f32_e32 v50, 0x3fb8aa3b, v50
	v_mul_f32_e32 v51, 0x3fb8aa3b, v51
	v_add_f32_e32 v49, 1.0, v49
	v_rcp_f32_e32 v49, v49
	v_exp_f32_e32 v52, v52
	v_exp_f32_e32 v50, v50
	v_exp_f32_e32 v51, v51
	v_mul_f32_e32 v40, 0x3fb8aa3b, v40
	v_mul_f32_e32 v45, 0x3fb8aa3b, v45
	v_exp_f32_e32 v40, v40
	v_exp_f32_e32 v45, v45
	v_add_f32_e32 v52, 1.0, v52
	v_add_f32_e32 v50, 1.0, v50
	v_add_f32_e32 v51, 1.0, v51
	v_rcp_f32_e32 v52, v52
	v_rcp_f32_e32 v50, v50
	v_rcp_f32_e32 v51, v51
	v_add_f32_e32 v40, 1.0, v40
	v_add_f32_e32 v45, 1.0, v45
	v_mul_f32_e32 v41, 0x3fb8aa3b, v41
	v_rcp_f32_e32 v40, v40
	v_rcp_f32_e32 v45, v45
	v_exp_f32_e32 v41, v41
	v_mul_f32_e32 v44, 0x3fb8aa3b, v44
	v_mul_f32_e32 v42, 0x3fb8aa3b, v42
	v_mul_f32_e32 v43, 0x3fb8aa3b, v43
	v_add_f32_e32 v41, 1.0, v41
	v_rcp_f32_e32 v41, v41
	v_exp_f32_e32 v44, v44
	v_exp_f32_e32 v42, v42
	v_exp_f32_e32 v43, v43
	v_mul_f32_e32 v32, 0x3fb8aa3b, v32
	v_mul_f32_e32 v37, 0x3fb8aa3b, v37
	v_exp_f32_e32 v32, v32
	v_exp_f32_e32 v37, v37
	v_add_f32_e32 v44, 1.0, v44
	v_add_f32_e32 v42, 1.0, v42
	s_nop 0
	v_pk_add_f32 v[60:61], v[226:227], 1.0 op_sel_hi:[1,0] neg_lo:[1,0] neg_hi:[1,0]
	v_pk_add_f32 v[62:63], v[230:231], 1.0 op_sel_hi:[1,0] neg_lo:[1,0] neg_hi:[1,0]
	v_pk_mul_f32 v[56:57], v[56:57], v[60:61]
	v_mul_f32_e32 v52, v52, v60
	v_cvt_pk_f16_f32 v72, v56, v57
	v_pk_add_f32 v[56:57], v[228:229], 1.0 op_sel_hi:[1,0] neg_lo:[1,0] neg_hi:[1,0]
	v_add_f32_e32 v43, 1.0, v43
	v_pk_mul_f32 v[58:59], v[58:59], v[56:57]
	v_rcp_f32_e32 v44, v44
	v_cvt_pk_f16_f32 v73, v58, v59
	v_pk_mul_f32 v[58:59], v[80:81], v[62:63]
	v_rcp_f32_e32 v42, v42
	v_cvt_pk_f16_f32 v74, v58, v59
	v_pk_add_f32 v[58:59], v[232:233], 1.0 op_sel_hi:[1,0] neg_lo:[1,0] neg_hi:[1,0]
	v_rcp_f32_e32 v43, v43
	v_pk_mul_f32 v[76:77], v[82:83], v[58:59]
	v_mul_f32_e32 v51, v51, v59
	v_cvt_pk_f16_f32 v75, v76, v77
	global_store_dwordx4 v[112:113], v[72:75], off offset:256
	v_add_f32_e32 v32, 1.0, v32
	v_add_f32_e32 v37, 1.0, v37
	v_mul_f32_e32 v72, v48, v62
	v_mul_f32_e32 v48, v53, v61
	v_mul_f32_e32 v53, 0x3fb8aa3b, v54
	v_exp_f32_e32 v53, v53
	v_mul_f32_e32 v54, v49, v63
	v_cvt_pk_f16_f32 v48, v52, v48
	v_mul_f32_e32 v33, 0x3fb8aa3b, v33
	v_add_f32_e32 v49, 1.0, v53
	v_mul_f32_e32 v53, 0x3fb8aa3b, v55
	v_exp_f32_e32 v53, v53
	v_rcp_f32_e32 v49, v49
	v_mul_f32_e32 v55, v50, v58
	v_cvt_pk_f16_f32 v51, v55, v51
	v_add_f32_e32 v53, 1.0, v53
	v_rcp_f32_e32 v53, v53
	v_mul_f32_e32 v49, v49, v56
	v_rcp_f32_e32 v32, v32
	v_rcp_f32_e32 v37, v37
	v_mul_f32_e32 v50, v53, v57
	v_cvt_pk_f16_f32 v49, v49, v50
	v_cvt_pk_f16_f32 v50, v72, v54
	global_store_dwordx4 v[114:115], v[48:51], off offset:256
	v_exp_f32_e32 v33, v33
	v_mul_f32_e32 v44, v44, v60
	v_mul_f32_e32 v48, v40, v62
	v_mul_f32_e32 v40, v45, v61
	v_mul_f32_e32 v45, 0x3fb8aa3b, v46
	v_exp_f32_e32 v45, v45
	v_mul_f32_e32 v46, v41, v63
	v_mul_f32_e32 v43, v43, v59
	v_cvt_pk_f16_f32 v40, v44, v40
	v_add_f32_e32 v41, 1.0, v45
	v_mul_f32_e32 v45, 0x3fb8aa3b, v47
	v_exp_f32_e32 v45, v45
	v_rcp_f32_e32 v41, v41
;     __device__ __forceinline__ void operator()(const AccT& acc, const pg8::Unit& u, int wr, int wc, int fr, int fq) const {
;     ...
;                     for (int m = 0; m < 4; ++m) {
;                         const f32x4 a = acc[ai][bj][m][0], b = acc[ai][bj][m][1]; float g[8];
; #pragma unroll
;                         for (int j = 0; j < 4; ++j) { g[j] = (1.f - l0[j]) * __builtin_amdgcn_rcpf(1.f + __expf(a[j])); g[4 + j] = (1.f - l1[j]) * __builtin_amdgcn_rcpf(1.f + __expf(b[j])); }
;                         u32x4 w; w.x = pk_h2(g[0], g[1]); w.y = pk_h2(g[2], g[3]); w.z = pk_h2(g[4], g[5]); w.w = pk_h2(g[6], g[7]);
;                         *(u32x4*)(G + (size_t)(row0 + ai * 128 + m * 16) * 2048 + col) = w;
;                     }
	v_mul_f32_e32 v47, v42, v58
	v_cvt_pk_f16_f32 v43, v47, v43
	v_add_f32_e32 v45, 1.0, v45
	v_rcp_f32_e32 v45, v45
	v_mul_f32_e32 v41, v41, v56
	v_add_f32_e32 v33, 1.0, v33
	v_rcp_f32_e32 v33, v33
	v_mul_f32_e32 v42, v45, v57
	v_cvt_pk_f16_f32 v41, v41, v42
	v_cvt_pk_f16_f32 v42, v48, v46
	global_store_dwordx4 v[104:105], v[40:43], off offset:256
	v_mul_f32_e32 v36, 0x3fb8aa3b, v36
	v_mul_f32_e32 v34, 0x3fb8aa3b, v34
	v_mul_f32_e32 v40, v32, v62
	v_mul_f32_e32 v32, v37, v61
	v_mul_f32_e32 v37, 0x3fb8aa3b, v38
	v_exp_f32_e32 v37, v37
	v_mul_f32_e32 v38, v33, v63
	v_mul_f32_e32 v35, 0x3fb8aa3b, v35
	v_exp_f32_e32 v36, v36
	v_add_f32_e32 v33, 1.0, v37
	v_mul_f32_e32 v37, 0x3fb8aa3b, v39
	v_exp_f32_e32 v34, v34
	v_exp_f32_e32 v37, v37
	v_exp_f32_e32 v35, v35
	v_mul_f32_e32 v24, 0x3fb8aa3b, v24
	v_mul_f32_e32 v29, 0x3fb8aa3b, v29
	v_exp_f32_e32 v24, v24
	v_exp_f32_e32 v29, v29
	v_add_f32_e32 v36, 1.0, v36
	v_add_f32_e32 v34, 1.0, v34
	v_add_f32_e32 v37, 1.0, v37
	v_add_f32_e32 v35, 1.0, v35
	v_rcp_f32_e32 v36, v36
	v_rcp_f32_e32 v33, v33
	v_rcp_f32_e32 v34, v34
	v_rcp_f32_e32 v37, v37
	v_rcp_f32_e32 v35, v35
	v_add_f32_e32 v24, 1.0, v24
	v_add_f32_e32 v29, 1.0, v29
	v_mul_f32_e32 v25, 0x3fb8aa3b, v25
	v_rcp_f32_e32 v24, v24
	v_rcp_f32_e32 v29, v29
	v_exp_f32_e32 v25, v25
	v_mul_f32_e32 v36, v36, v60
	v_mul_f32_e32 v33, v33, v56
	v_mul_f32_e32 v39, v34, v58
	v_mul_f32_e32 v34, v37, v57
	v_mul_f32_e32 v35, v35, v59
	v_cvt_pk_f16_f32 v32, v36, v32
	v_cvt_pk_f16_f32 v33, v33, v34
	v_cvt_pk_f16_f32 v34, v40, v38
	v_cvt_pk_f16_f32 v35, v39, v35
	global_store_dwordx4 v[96:97], v[32:35], off offset:256
	v_add_f32_e32 v25, 1.0, v25
	v_rcp_f32_e32 v25, v25
	v_mul_f32_e32 v32, v24, v62
	v_mul_f32_e32 v24, v29, v61
	v_mul_f32_e32 v29, 0x3fb8aa3b, v30
	v_exp_f32_e32 v29, v29
	v_mul_f32_e32 v28, 0x3fb8aa3b, v28
	v_mul_f32_e32 v26, 0x3fb8aa3b, v26
	v_mul_f32_e32 v30, v25, v63
	v_add_f32_e32 v25, 1.0, v29
	v_mul_f32_e32 v29, 0x3fb8aa3b, v31
	v_mul_f32_e32 v27, 0x3fb8aa3b, v27
	v_exp_f32_e32 v28, v28
	v_exp_f32_e32 v26, v26
	v_exp_f32_e32 v29, v29
	v_exp_f32_e32 v27, v27
	v_mul_f32_e32 v16, 0x3fb8aa3b, v16
	v_mul_f32_e32 v21, 0x3fb8aa3b, v21
	v_exp_f32_e32 v16, v16
	v_exp_f32_e32 v21, v21
	v_add_f32_e32 v28, 1.0, v28
	v_add_f32_e32 v26, 1.0, v26
	v_add_f32_e32 v29, 1.0, v29
	v_add_f32_e32 v27, 1.0, v27
	v_rcp_f32_e32 v28, v28
	v_rcp_f32_e32 v25, v25
	v_rcp_f32_e32 v26, v26
	v_rcp_f32_e32 v29, v29
	v_rcp_f32_e32 v27, v27
	v_add_f32_e32 v16, 1.0, v16
	v_add_f32_e32 v21, 1.0, v21
	v_mul_f32_e32 v17, 0x3fb8aa3b, v17
	v_rcp_f32_e32 v16, v16
	v_rcp_f32_e32 v21, v21
	v_exp_f32_e32 v17, v17
	s_mov_b64 s[4:5], 0x80000
	v_mul_f32_e32 v28, v28, v60
	v_mul_f32_e32 v25, v25, v56
	v_mul_f32_e32 v31, v26, v58
	v_mul_f32_e32 v26, v29, v57
	v_mul_f32_e32 v27, v27, v59
	v_lshl_add_u64 v[70:71], v[112:113], 0, s[4:5]
	v_cvt_pk_f16_f32 v24, v28, v24
	v_cvt_pk_f16_f32 v25, v25, v26
	v_cvt_pk_f16_f32 v26, v32, v30
	v_cvt_pk_f16_f32 v27, v31, v27
	global_store_dwordx4 v[70:71], v[24:27], off offset:256
	v_add_f32_e32 v17, 1.0, v17
	v_rcp_f32_e32 v17, v17
	v_mul_f32_e32 v24, v16, v62
	v_mul_f32_e32 v16, v21, v61
	v_mul_f32_e32 v21, 0x3fb8aa3b, v22
	v_exp_f32_e32 v21, v21
	v_mul_f32_e32 v20, 0x3fb8aa3b, v20
	v_mul_f32_e32 v18, 0x3fb8aa3b, v18
	v_mul_f32_e32 v22, v17, v63
	v_add_f32_e32 v17, 1.0, v21
	v_mul_f32_e32 v21, 0x3fb8aa3b, v23
	v_mul_f32_e32 v19, 0x3fb8aa3b, v19
	v_exp_f32_e32 v20, v20
	v_exp_f32_e32 v18, v18
	v_exp_f32_e32 v21, v21
	v_exp_f32_e32 v19, v19
	v_mul_f32_e32 v8, 0x3fb8aa3b, v8
	v_mul_f32_e32 v13, 0x3fb8aa3b, v13
	v_exp_f32_e32 v8, v8
	v_exp_f32_e32 v13, v13
	v_add_f32_e32 v20, 1.0, v20
	v_add_f32_e32 v18, 1.0, v18
	v_add_f32_e32 v21, 1.0, v21
	v_add_f32_e32 v19, 1.0, v19
	v_rcp_f32_e32 v20, v20
	v_rcp_f32_e32 v17, v17
	v_rcp_f32_e32 v18, v18
	v_rcp_f32_e32 v21, v21
	v_rcp_f32_e32 v19, v19
	v_add_f32_e32 v8, 1.0, v8
	v_add_f32_e32 v13, 1.0, v13
	v_mul_f32_e32 v9, 0x3fb8aa3b, v9
	v_rcp_f32_e32 v8, v8
	v_rcp_f32_e32 v13, v13
	v_exp_f32_e32 v9, v9
	v_mul_f32_e32 v20, v20, v60
	v_mul_f32_e32 v17, v17, v56
	v_mul_f32_e32 v23, v18, v58
	v_mul_f32_e32 v18, v21, v57
	v_mul_f32_e32 v19, v19, v59
	v_lshl_add_u64 v[68:69], v[112:113], 0, s[40:41]
	v_cvt_pk_f16_f32 v16, v20, v16
	v_cvt_pk_f16_f32 v17, v17, v18
	v_cvt_pk_f16_f32 v18, v24, v22
	v_cvt_pk_f16_f32 v19, v23, v19
	global_store_dwordx4 v[68:69], v[16:19], off offset:256
	v_add_f32_e32 v9, 1.0, v9
	v_rcp_f32_e32 v9, v9
	v_mul_f32_e32 v16, v8, v62
	v_mul_f32_e32 v8, v13, v61
	v_mul_f32_e32 v13, 0x3fb8aa3b, v14
	v_exp_f32_e32 v13, v13
	v_mul_f32_e32 v12, 0x3fb8aa3b, v12
	v_mul_f32_e32 v10, 0x3fb8aa3b, v10
	v_mul_f32_e32 v14, v9, v63
	v_add_f32_e32 v9, 1.0, v13
	v_mul_f32_e32 v13, 0x3fb8aa3b, v15
	v_mul_f32_e32 v11, 0x3fb8aa3b, v11
	v_exp_f32_e32 v12, v12
	v_exp_f32_e32 v10, v10
	v_exp_f32_e32 v13, v13
	v_exp_f32_e32 v11, v11
	v_mul_f32_e32 v0, 0x3fb8aa3b, v0
	v_mul_f32_e32 v5, 0x3fb8aa3b, v5
	v_exp_f32_e32 v0, v0
	v_exp_f32_e32 v5, v5
	v_add_f32_e32 v12, 1.0, v12
	v_add_f32_e32 v10, 1.0, v10
	v_add_f32_e32 v13, 1.0, v13
	v_add_f32_e32 v11, 1.0, v11
	v_rcp_f32_e32 v12, v12
	v_rcp_f32_e32 v9, v9
	v_rcp_f32_e32 v10, v10
	v_rcp_f32_e32 v13, v13
	v_rcp_f32_e32 v11, v11
	v_add_f32_e32 v0, 1.0, v0
	v_add_f32_e32 v5, 1.0, v5
	v_mul_f32_e32 v1, 0x3fb8aa3b, v1
	v_rcp_f32_e32 v0, v0
	v_rcp_f32_e32 v5, v5
	v_exp_f32_e32 v1, v1
	v_mul_f32_e32 v12, v12, v60
	v_mul_f32_e32 v9, v9, v56
	v_mul_f32_e32 v15, v10, v58
	v_mul_f32_e32 v10, v13, v57
	v_mul_f32_e32 v11, v11, v59
	v_lshl_add_u64 v[66:67], v[112:113], 0, s[42:43]
	v_cvt_pk_f16_f32 v8, v12, v8
	v_cvt_pk_f16_f32 v9, v9, v10
	v_cvt_pk_f16_f32 v10, v16, v14
	v_cvt_pk_f16_f32 v11, v15, v11
	global_store_dwordx4 v[66:67], v[8:11], off offset:256
	v_add_f32_e32 v1, 1.0, v1
	v_rcp_f32_e32 v1, v1
	v_mul_f32_e32 v8, v0, v62
	v_mul_f32_e32 v0, v5, v61
	v_mul_f32_e32 v5, 0x3fb8aa3b, v6
	v_exp_f32_e32 v5, v5
	v_mul_f32_e32 v4, 0x3fb8aa3b, v4
	v_mul_f32_e32 v2, 0x3fb8aa3b, v2
	v_mul_f32_e32 v6, v1, v63
	v_add_f32_e32 v1, 1.0, v5
	v_mul_f32_e32 v5, 0x3fb8aa3b, v7
	v_mul_f32_e32 v3, 0x3fb8aa3b, v3
	v_exp_f32_e32 v4, v4
	v_exp_f32_e32 v2, v2
	v_exp_f32_e32 v5, v5
	v_exp_f32_e32 v3, v3
	v_add_f32_e32 v4, 1.0, v4
	v_add_f32_e32 v2, 1.0, v2
	v_add_f32_e32 v5, 1.0, v5
	v_add_f32_e32 v3, 1.0, v3
	v_rcp_f32_e32 v4, v4
	v_rcp_f32_e32 v1, v1
	v_rcp_f32_e32 v2, v2
	v_rcp_f32_e32 v5, v5
	v_rcp_f32_e32 v3, v3
	v_mul_f32_e32 v4, v4, v60
	v_mul_f32_e32 v1, v1, v56
	v_mul_f32_e32 v7, v2, v58
	v_mul_f32_e32 v2, v5, v57
	v_mul_f32_e32 v3, v3, v59
	v_lshl_add_u64 v[64:65], v[112:113], 0, s[44:45]
	v_cvt_pk_f16_f32 v0, v4, v0
	v_cvt_pk_f16_f32 v1, v1, v2
	v_cvt_pk_f16_f32 v2, v8, v6
	v_cvt_pk_f16_f32 v3, v7, v3
	global_store_dwordx4 v[64:65], v[0:3], off offset:256
	s_branch .LBB0_231
